# indexer score unit: the four Q-fragment staging loads issued together into dead register quads with counted waits (were four dependent load/wait/ds_write round trips per 32-query group)
# baseline (speedup 1.0000x reference)
; __device__ __forceinline__ int fresh_lane() { int l; asm volatile("v_mbcnt_lo_u32_b32 %0, -1, 0\n\tv_mbcnt_hi_u32_b32 %0, -1, %0" : "=v"(l)); return l; }
; __device__ __forceinline__ void score_unit_prompt(const Ctx& C, int b, int g, unsigned char* lds) {
;     const int lane = fresh_lane(), tid = C.wave * 64 + lane, r32 = lane & 31, hi = lane >> 5;
;     const bf16_t* qib = (const bf16_t*)(C.ws + WS_QI); const bf16_t* kib = (const bf16_t*)(C.ws + WS_KI);
; #pragma unroll
;     for (int j = 0; j < 4; ++j) { const int id = tid + 512 * j, c = id >> 5, r = id & 31;
;         *(u32x4*)(lds + id * 16) = *(const u32x4*)(qib + (size_t)(b * SEQ + 32 * g + r) * 512 + c * 8); }
;     __syncthreads();
;     const int qrow0 = b * SEQ + 32 * g;
;     float w[8]; load8_f32((const float*)(C.ws + WS_IW) + (size_t)(qrow0 + r32) * 8, w);
;     float* stg = (float*)(lds + 32768 + C.wave * 8704);
;     float* sout = (float*)(C.ws + WS_SC) + (size_t)(qrow0 + (lane >> 4)) * SEQ + (lane & 15) * 4;
;     const int nt = (g >> 1) + 1;
;     const int ntp = ((32 * g + 32 + 511) >> 9) << 3;
;     const int tq = 32 * g + r32;
;     const unsigned char* qbase = lds + hi * 512 + r32 * 16;
;     const unsigned qaddr = (unsigned)(uintptr_t)qbase;
;     const bf16_t* kp0 = kib + (size_t)(b * SEQ + r32) * 64 + hi * 8;
;     bf16x8 kf[4][2];
;     { const bf16_t* kp = kp0 + (size_t)((C.wave < nt) ? C.wave : 0) * 4096;
; #pragma unroll
;       for (int d0 = 0; d0 < 4; ++d0) { kf[d0][0] = *(const bf16x8*)(kp + d0 * 16); kf[d0][1] = *(const bf16x8*)(kp + 32 * 64 + d0 * 16); } }
;     for (int kt = C.wave; kt < ntp; kt += NWAVES) {
;         bf16x8 kn[4][2];
;         { const bf16_t* kp = kp0 + (size_t)((kt + NWAVES < nt) ? kt + NWAVES : kt) * 4096;
; #pragma unroll
;           for (int d0 = 0; d0 < 4; ++d0) { kn[d0][0] = *(const bf16x8*)(kp + d0 * 16); kn[d0][1] = *(const bf16x8*)(kp + 32 * 64 + d0 * 16); } }
.LBB0_785:
	s_andn2_b64 vcc, exec, s[4:5]
	s_cbranch_vccnz .LBB0_2034
	s_add_i32 s0, s2, 0xffffff80
	s_lshr_b32 s0, s0, 1
	s_and_b32 s1, s2, 1
	s_sub_i32 s10, 0xff, s0
	s_lshl_b32 s6, s1, 13
	s_lshl_b32 s7, s10, 5
	s_waitcnt vmcnt(1)
	v_mbcnt_lo_u32_b32 v3, -1, 0
	v_mbcnt_hi_u32_b32 v3, -1, v3
	s_or_b32 s4, s7, s6
	v_and_b32_e32 v2, 31, v3
	v_or_b32_e32 v4, s4, v2
	v_add_u32_e32 v5, s89, v3
	v_lshlrev_b32_e32 v0, 10, v4
	v_lshl_add_u64 v[10:11], s[78:79], 0, v[0:1]
	v_ashrrev_i32_e32 v0, 2, v5
	s_waitcnt vmcnt(0)
	v_and_b32_e32 v6, -8, v0
	v_ashrrev_i32_e32 v7, 31, v6
	v_lshl_add_u64 v[6:7], v[6:7], 1, v[10:11]
	global_load_dwordx4 v[6:9], v[6:7], off
	v_lshl_add_u32 v0, v5, 4, 0
	s_add_i32 s5, s7, 0x21f
	s_lshr_b32 s5, s5, 6
	s_and_b32 s8, s5, 0xf8
	s_cmp_ge_u32 s76, s8
	v_add_u32_e32 v12, 0x200, v5
	v_ashrrev_i32_e32 v36, 2, v12
	v_and_b32_e32 v36, -8, v36
	v_ashrrev_i32_e32 v37, 31, v36
	v_lshl_add_u64 v[36:37], v[36:37], 1, v[10:11]
	global_load_dwordx4 v[36:39], v[36:37], off
	v_lshl_add_u32 v12, v12, 4, 0
	v_add_u32_e32 v13, 0x400, v5
	v_ashrrev_i32_e32 v40, 2, v13
	v_and_b32_e32 v40, -8, v40
	v_ashrrev_i32_e32 v41, 31, v40
	v_lshl_add_u64 v[40:41], v[40:41], 1, v[10:11]
	global_load_dwordx4 v[40:43], v[40:41], off
	v_lshl_add_u32 v13, v13, 4, 0
	v_add_u32_e32 v14, 0x600, v5
	v_ashrrev_i32_e32 v44, 2, v14
	v_and_b32_e32 v44, -8, v44
	v_ashrrev_i32_e32 v45, 31, v44
	v_lshl_add_u64 v[44:45], v[44:45], 1, v[10:11]
	global_load_dwordx4 v[44:47], v[44:45], off
	v_lshl_add_u32 v14, v14, 4, 0
	s_waitcnt vmcnt(3)
	ds_write_b128 v0, v[6:9]
	s_waitcnt vmcnt(2)
	ds_write_b128 v12, v[36:39]
	s_waitcnt vmcnt(1)
	ds_write_b128 v13, v[40:43]
	s_waitcnt vmcnt(0)
	ds_write_b128 v14, v[44:47]
	s_waitcnt lgkmcnt(0)
	s_barrier
	s_cbranch_scc1 .LBB0_793
	v_ashrrev_i32_e32 v10, 5, v3
	v_lshlrev_b32_e32 v0, 5, v4
	global_load_dwordx4 v[50:53], v0, s[96:97]
	global_load_dwordx4 v[54:57], v0, s[96:97] offset:16
	v_ashrrev_i32_e32 v11, 4, v3
	v_lshlrev_b32_e32 v0, 9, v10
	v_lshlrev_b32_e32 v6, 4, v2
	v_add_u32_e32 v4, s4, v11
	v_add3_u32 v211, 0, v0, v6
	v_or_b32_e32 v0, s6, v2
	v_readlane_b32 s4, v250, 57
	v_lshlrev_b32_e32 v0, 7, v0
	v_readlane_b32 s5, v250, 58
	v_ashrrev_i32_e32 v5, 31, v4
	s_lshr_b32 s9, s10, 1
	v_lshl_add_u64 v[6:7], s[4:5], 0, v[0:1]
	v_lshlrev_b32_e32 v8, 3, v10
	v_readlane_b32 s4, v249, 0
	v_lshlrev_b64 v[4:5], 15, v[4:5]
	v_ashrrev_i32_e32 v9, 31, v8
	v_lshlrev_b32_e32 v0, 4, v3
	s_cmp_le_u32 s76, s9
	v_readlane_b32 s5, v249, 1
	v_lshl_add_u64 v[154:155], v[8:9], 1, v[6:7]
	v_lshl_add_u64 v[4:5], s[90:91], 0, v[4:5]
	v_and_b32_e32 v0, 0xf0, v0
	s_cselect_b32 s5, s5, 0
	s_cselect_b32 s4, s4, 0
	v_lshl_add_u64 v[156:157], v[4:5], 0, v[0:1]
	v_lshl_add_u64 v[4:5], s[4:5], 1, v[154:155]
	s_movk_i32 s4, 0x1000
	v_add_co_u32_e32 v6, vcc, s4, v4
	v_or_b32_e32 v212, s7, v2
	s_nop 0
	v_addc_co_u32_e32 v7, vcc, 0, v5, vcc
	global_load_dwordx4 v[90:93], v[6:7], off offset:96
	global_load_dwordx4 v[106:109], v[4:5], off offset:96
	global_load_dwordx4 v[94:97], v[6:7], off offset:64
	global_load_dwordx4 v[110:113], v[4:5], off offset:64
	global_load_dwordx4 v[98:101], v[6:7], off offset:32
	global_load_dwordx4 v[114:117], v[4:5], off offset:32
	global_load_dwordx4 v[102:105], v[6:7], off
	global_load_dwordx4 v[118:121], v[4:5], off
	v_mul_u32_u24_e32 v2, 0x110, v2
	v_lshlrev_b32_e32 v3, 4, v10
	v_readlane_b32 s4, v249, 12
	v_lshlrev_b32_e32 v213, 2, v10
	v_subrev_u32_e32 v214, 32, v212
	v_add3_u32 v215, s4, v2, v3
	v_add_u32_e32 v0, s4, v0
	s_movk_i32 s4, 0x110
	v_mul_lo_u32 v2, v11, s4
	v_add_u32_e32 v216, v0, v2
	s_mov_b32 s4, s89
	s_mov_b32 s11, s76
	s_branch .LBB0_789
